# K1: the two 64-step serial running-sum loops (one LDS read + add per step) replaced by 6-step DPP inclusive scans
# speedup vs baseline: 1.0736x; 1.0132x over previous
.LBB0_483:
	s_or_b64 exec, exec, s[0:1]
	s_mul_i32 s1, s41, 0x500
	v_readlane_b32 s2, v239, 9
	s_mul_hi_u32 s0, s41, 0x500
	s_add_u32 s38, s2, s1
	v_readlane_b32 s1, v239, 10
	s_addc_u32 s39, s1, s0
	s_waitcnt lgkmcnt(0)
	s_barrier
	s_and_saveexec_b64 s[42:43], vcc
	s_cbranch_execz .LBB0_489
	v_cmp_lt_i32_e64 s[0:1], -1, v18
	ds_read_b32 v0, v24 offset:27904
	s_waitcnt lgkmcnt(0)
	v_mov_b32_e32 v3, v0
	s_nop 1
	v_add_f32_dpp v0, v3, v0 row_shr:1 row_mask:0xf bank_mask:0xf
	s_nop 0
	v_mov_b32_e32 v3, v0
	s_nop 1
	v_add_f32_dpp v0, v3, v0 row_shr:2 row_mask:0xf bank_mask:0xf
	s_nop 0
	v_mov_b32_e32 v3, v0
	s_nop 1
	v_add_f32_dpp v0, v3, v0 row_shr:4 row_mask:0xf bank_mask:0xf
	s_nop 0
	v_mov_b32_e32 v3, v0
	s_nop 1
	v_add_f32_dpp v0, v3, v0 row_shr:8 row_mask:0xf bank_mask:0xf
	s_nop 0
	v_mov_b32_e32 v3, v0
	s_nop 1
	v_add_f32_dpp v0, v3, v0 row_bcast:15 row_mask:0xa bank_mask:0xf
	s_nop 0
	v_mov_b32_e32 v3, v0
	s_nop 1
	v_add_f32_dpp v0, v3, v0 row_bcast:31 row_mask:0xc bank_mask:0xf
	s_nop 0
.LBB0_488:
	ds_read_b32 v2, v24 offset:28160
	v_ashrrev_i32_e32 v19, 31, v18
	s_waitcnt lgkmcnt(0)
	v_sub_f32_e32 v2, v2, v0
	ds_write_b32 v24, v2 offset:27648
	v_lshl_add_u64 v[2:3], v[18:19], 2, s[38:39]
	global_store_dword v[2:3], v0, off

.LBB0_532:
	s_or_b64 exec, exec, s[42:43]
	s_waitcnt lgkmcnt(0)
	s_barrier
	s_and_saveexec_b64 s[0:1], vcc
	s_cbranch_execz .LBB0_538
	v_cmp_lt_i32_e32 vcc, -1, v40
	ds_read_b32 v2, v0 offset:52736
	s_waitcnt lgkmcnt(0)
	v_mov_b32_e32 v4, v2
	s_nop 1
	v_add_f32_dpp v2, v4, v2 row_shr:1 row_mask:0xf bank_mask:0xf
	s_nop 0
	v_mov_b32_e32 v4, v2
	s_nop 1
	v_add_f32_dpp v2, v4, v2 row_shr:2 row_mask:0xf bank_mask:0xf
	s_nop 0
	v_mov_b32_e32 v4, v2
	s_nop 1
	v_add_f32_dpp v2, v4, v2 row_shr:4 row_mask:0xf bank_mask:0xf
	s_nop 0
	v_mov_b32_e32 v4, v2
	s_nop 1
	v_add_f32_dpp v2, v4, v2 row_shr:8 row_mask:0xf bank_mask:0xf
	s_nop 0
	v_mov_b32_e32 v4, v2
	s_nop 1
	v_add_f32_dpp v2, v4, v2 row_bcast:15 row_mask:0xa bank_mask:0xf
	s_nop 0
	v_mov_b32_e32 v4, v2
	s_nop 1
	v_add_f32_dpp v2, v4, v2 row_bcast:31 row_mask:0xc bank_mask:0xf
	s_nop 0
.LBB0_537:
	ds_read_b32 v3, v0 offset:52480
	s_waitcnt lgkmcnt(0)
	ds_write2st64_b32 v0, v2, v3 offset0:204 offset1:207
	v_mul_f32_e32 v2, 0x3fb8aa3b, v2
	v_exp_f32_e32 v2, v2
	s_nop 0
	v_mul_f32_e32 v2, v2, v3
	ds_write_b32 v0, v2 offset:53248
